# GEMM K-loops: MFMAs reordered k-innermost (same-accumulator pairs back-to-back) on top of SwiGLU epilogue rewrite
# speedup vs baseline: 1.0069x; 1.0069x over previous
.LBB0_32:
	s_add_u32 s28, s54, 0xfff80080
	s_addc_u32 s29, s55, -1
	s_add_i32 s30, 0, 0x10000
	s_cmp_eq_u32 s27, 28
	s_cselect_b32 s79, s13, s29
	s_cselect_b32 s78, s16, s28
	s_cselect_b32 s69, s9, s26
	s_cselect_b32 s68, s24, s25
	s_add_i32 s31, 0, 0x14000
	v_add_u32_e32 v142, s30, v184
	v_add_u32_e32 v172, s31, v184
	ds_read_b128 v[130:133], v142
	ds_read_b128 v[134:137], v142 offset:1024
	ds_read_b128 v[138:141], v142 offset:2048
	ds_read_b128 v[142:145], v142 offset:3072
	ds_read_b128 v[146:149], v172
	ds_read_b128 v[150:153], v172 offset:1024
	ds_read_b128 v[154:157], v172 offset:2048
	ds_read_b128 v[172:175], v172 offset:3072
	v_lshl_add_u64 v[212:213], s[54:55], 0, v[166:167]
	s_add_i32 m0, s42, 0xc000
	ds_read_b128 v[176:179], v186
	ds_read_b128 v[180:183], v186 offset:1024
	ds_read_b128 v[188:191], v186 offset:2048
	ds_read_b128 v[192:195], v186 offset:3072
	ds_read_b128 v[196:199], v186 offset:4096
	ds_read_b128 v[200:203], v186 offset:5120
	ds_read_b128 v[204:207], v186 offset:6144
	ds_read_b128 v[208:211], v186 offset:7168
	global_load_lds_dwordx4 v[212:213], off
	v_lshl_add_u64 v[212:213], s[54:55], 0, v[168:169]
	s_add_i32 m0, s42, 0xe000
	s_nop 0
	global_load_lds_dwordx4 v[212:213], off
	s_waitcnt vmcnt(8)
	s_waitcnt lgkmcnt(0)
	s_barrier
	s_setprio 1
	s_waitcnt lgkmcnt(0)
	v_mfma_f32_16x16x32_bf16 v[126:129], v[130:133], v[176:179], v[126:129]
	v_mfma_f32_16x16x32_bf16 v[126:129], v[134:137], v[180:183], v[126:129]
	v_mfma_f32_16x16x32_bf16 v[122:125], v[138:141], v[176:179], v[122:125]
	v_mfma_f32_16x16x32_bf16 v[122:125], v[142:145], v[180:183], v[122:125]
	v_mfma_f32_16x16x32_bf16 v[110:113], v[130:133], v[188:191], v[110:113]
	v_mfma_f32_16x16x32_bf16 v[110:113], v[134:137], v[192:195], v[110:113]
	v_mfma_f32_16x16x32_bf16 v[106:109], v[138:141], v[188:191], v[106:109]
	v_mfma_f32_16x16x32_bf16 v[106:109], v[142:145], v[192:195], v[106:109]
	v_mfma_f32_16x16x32_bf16 v[94:97], v[130:133], v[196:199], v[94:97]
	v_mfma_f32_16x16x32_bf16 v[94:97], v[134:137], v[200:203], v[94:97]
	v_mfma_f32_16x16x32_bf16 v[90:93], v[138:141], v[196:199], v[90:93]
	v_mfma_f32_16x16x32_bf16 v[90:93], v[142:145], v[200:203], v[90:93]
	v_mfma_f32_16x16x32_bf16 v[78:81], v[130:133], v[204:207], v[78:81]
	v_mfma_f32_16x16x32_bf16 v[78:81], v[134:137], v[208:211], v[78:81]
	v_mfma_f32_16x16x32_bf16 v[74:77], v[138:141], v[204:207], v[74:77]
	v_mfma_f32_16x16x32_bf16 v[74:77], v[142:145], v[208:211], v[74:77]
	s_setprio 0
	s_setprio 1
	v_mfma_f32_16x16x32_bf16 v[118:121], v[146:149], v[176:179], v[118:121]
	v_mfma_f32_16x16x32_bf16 v[118:121], v[150:153], v[180:183], v[118:121]
	v_mfma_f32_16x16x32_bf16 v[114:117], v[154:157], v[176:179], v[114:117]
	v_mfma_f32_16x16x32_bf16 v[114:117], v[172:175], v[180:183], v[114:117]
	v_mfma_f32_16x16x32_bf16 v[102:105], v[146:149], v[188:191], v[102:105]
	v_mfma_f32_16x16x32_bf16 v[102:105], v[150:153], v[192:195], v[102:105]
	v_mfma_f32_16x16x32_bf16 v[98:101], v[154:157], v[188:191], v[98:101]
	v_mfma_f32_16x16x32_bf16 v[98:101], v[172:175], v[192:195], v[98:101]
	v_mfma_f32_16x16x32_bf16 v[86:89], v[146:149], v[196:199], v[86:89]
	v_mfma_f32_16x16x32_bf16 v[86:89], v[150:153], v[200:203], v[86:89]
	v_mfma_f32_16x16x32_bf16 v[82:85], v[154:157], v[196:199], v[82:85]
	v_mfma_f32_16x16x32_bf16 v[82:85], v[172:175], v[200:203], v[82:85]
	v_mfma_f32_16x16x32_bf16 v[70:73], v[146:149], v[204:207], v[70:73]
	v_mfma_f32_16x16x32_bf16 v[70:73], v[150:153], v[208:211], v[70:73]
	v_mfma_f32_16x16x32_bf16 v[66:69], v[154:157], v[204:207], v[66:69]
	v_mfma_f32_16x16x32_bf16 v[66:69], v[172:175], v[208:211], v[66:69]
	s_setprio 0
	s_barrier
	s_add_i32 s28, s30, s11
	v_lshl_add_u64 v[212:213], s[68:69], 0, v[160:161]
	s_mov_b32 m0, s28
	ds_read_b128 v[176:179], v186 offset:16384
	ds_read_b128 v[180:183], v186 offset:17408
	ds_read_b128 v[188:191], v186 offset:18432
	ds_read_b128 v[192:195], v186 offset:19456
	ds_read_b128 v[196:199], v186 offset:20480
	ds_read_b128 v[200:203], v186 offset:21504
	ds_read_b128 v[204:207], v186 offset:22528
	ds_read_b128 v[208:211], v186 offset:23552
	global_load_lds_dwordx4 v[212:213], off
	s_add_i32 m0, s28, 0x2000
	s_add_u32 s28, s68, 0x80000
	v_lshl_add_u64 v[232:233], s[68:69], 0, v[164:165]
	s_addc_u32 s29, s69, 0
	s_add_i32 s30, s31, s11
	global_load_lds_dwordx4 v[232:233], off
	v_lshl_add_u64 v[234:235], s[28:29], 0, v[160:161]
	s_mov_b32 m0, s30
	v_lshl_add_u64 v[236:237], s[78:79], 0, v[162:163]
	global_load_lds_dwordx4 v[234:235], off
	v_lshl_add_u64 v[234:235], s[28:29], 0, v[164:165]
	s_add_i32 m0, s30, 0x2000
	s_nop 0
	global_load_lds_dwordx4 v[234:235], off
	v_lshl_add_u64 v[234:235], s[78:79], 0, v[158:159]
	s_mov_b32 m0, s42
	s_nop 0
	global_load_lds_dwordx4 v[234:235], off
	s_mov_b32 m0, s57
	s_nop 0
	global_load_lds_dwordx4 v[236:237], off
	s_waitcnt vmcnt(8)
	s_waitcnt lgkmcnt(0)
	s_barrier
	s_setprio 1
	s_waitcnt lgkmcnt(0)
	v_mfma_f32_16x16x32_bf16 v[62:65], v[130:133], v[176:179], v[62:65]
	v_mfma_f32_16x16x32_bf16 v[62:65], v[134:137], v[180:183], v[62:65]
	v_mfma_f32_16x16x32_bf16 v[58:61], v[138:141], v[176:179], v[58:61]
	v_mfma_f32_16x16x32_bf16 v[58:61], v[142:145], v[180:183], v[58:61]
	v_mfma_f32_16x16x32_bf16 v[46:49], v[130:133], v[188:191], v[46:49]
	v_mfma_f32_16x16x32_bf16 v[46:49], v[134:137], v[192:195], v[46:49]
	v_mfma_f32_16x16x32_bf16 v[42:45], v[138:141], v[188:191], v[42:45]
	v_mfma_f32_16x16x32_bf16 v[42:45], v[142:145], v[192:195], v[42:45]
	v_mfma_f32_16x16x32_bf16 v[30:33], v[130:133], v[196:199], v[30:33]
	v_mfma_f32_16x16x32_bf16 v[30:33], v[134:137], v[200:203], v[30:33]
	v_mfma_f32_16x16x32_bf16 v[26:29], v[138:141], v[196:199], v[26:29]
	v_mfma_f32_16x16x32_bf16 v[26:29], v[142:145], v[200:203], v[26:29]
	v_mfma_f32_16x16x32_bf16 v[14:17], v[130:133], v[204:207], v[14:17]
	v_mfma_f32_16x16x32_bf16 v[14:17], v[134:137], v[208:211], v[14:17]
	v_mfma_f32_16x16x32_bf16 v[10:13], v[138:141], v[204:207], v[10:13]
	v_mfma_f32_16x16x32_bf16 v[10:13], v[142:145], v[208:211], v[10:13]
	s_setprio 0
	s_setprio 1
	v_mfma_f32_16x16x32_bf16 v[54:57], v[146:149], v[176:179], v[54:57]
	v_mfma_f32_16x16x32_bf16 v[54:57], v[150:153], v[180:183], v[54:57]
	v_mfma_f32_16x16x32_bf16 v[50:53], v[154:157], v[176:179], v[50:53]
	v_mfma_f32_16x16x32_bf16 v[50:53], v[172:175], v[180:183], v[50:53]
	v_mfma_f32_16x16x32_bf16 v[38:41], v[146:149], v[188:191], v[38:41]
	v_mfma_f32_16x16x32_bf16 v[38:41], v[150:153], v[192:195], v[38:41]
	v_mfma_f32_16x16x32_bf16 v[34:37], v[154:157], v[188:191], v[34:37]
	v_mfma_f32_16x16x32_bf16 v[34:37], v[172:175], v[192:195], v[34:37]
	v_mfma_f32_16x16x32_bf16 v[22:25], v[146:149], v[196:199], v[22:25]
	v_mfma_f32_16x16x32_bf16 v[22:25], v[150:153], v[200:203], v[22:25]
	v_mfma_f32_16x16x32_bf16 v[18:21], v[154:157], v[196:199], v[18:21]
	v_mfma_f32_16x16x32_bf16 v[18:21], v[172:175], v[200:203], v[18:21]
	v_mfma_f32_16x16x32_bf16 v[6:9], v[146:149], v[204:207], v[6:9]
	v_mfma_f32_16x16x32_bf16 v[6:9], v[150:153], v[208:211], v[6:9]
	v_mfma_f32_16x16x32_bf16 v[2:5], v[154:157], v[204:207], v[2:5]
	v_mfma_f32_16x16x32_bf16 v[2:5], v[172:175], v[208:211], v[2:5]
	s_setprio 0
	s_barrier
	s_add_i32 s30, 0, 0x18000
	s_add_i32 s31, 0, 0x1c000
	v_add_u32_e32 v142, s30, v184
	v_add_u32_e32 v172, s31, v184
	ds_read_b128 v[130:133], v142
	ds_read_b128 v[134:137], v142 offset:1024
	ds_read_b128 v[138:141], v142 offset:2048
	ds_read_b128 v[142:145], v142 offset:3072
	ds_read_b128 v[146:149], v172
	ds_read_b128 v[150:153], v172 offset:1024
	ds_read_b128 v[154:157], v172 offset:2048
	ds_read_b128 v[172:175], v172 offset:3072
	s_add_u32 s28, s78, 0x80000
	s_addc_u32 s29, s79, 0
	s_mov_b32 m0, s67
	v_lshl_add_u64 v[238:239], s[28:29], 0, v[158:159]
	ds_read_b128 v[176:179], v186 offset:32768
	ds_read_b128 v[180:183], v186 offset:33792
	ds_read_b128 v[188:191], v186 offset:34816
	ds_read_b128 v[192:195], v186 offset:35840
	ds_read_b128 v[196:199], v186 offset:36864
	ds_read_b128 v[200:203], v186 offset:37888
	ds_read_b128 v[204:207], v186 offset:38912
	ds_read_b128 v[208:211], v186 offset:39936
	global_load_lds_dwordx4 v[238:239], off
	v_lshl_add_u64 v[238:239], s[28:29], 0, v[162:163]
	s_mov_b32 m0, s72
	s_nop 0
	global_load_lds_dwordx4 v[238:239], off
	s_waitcnt vmcnt(8)
	s_waitcnt lgkmcnt(0)
	s_barrier
	s_setprio 1
	s_waitcnt lgkmcnt(0)
	v_mfma_f32_16x16x32_bf16 v[126:129], v[130:133], v[176:179], v[126:129]
	v_mfma_f32_16x16x32_bf16 v[126:129], v[134:137], v[180:183], v[126:129]
	v_mfma_f32_16x16x32_bf16 v[122:125], v[138:141], v[176:179], v[122:125]
	v_mfma_f32_16x16x32_bf16 v[122:125], v[142:145], v[180:183], v[122:125]
	v_mfma_f32_16x16x32_bf16 v[110:113], v[130:133], v[188:191], v[110:113]
	v_mfma_f32_16x16x32_bf16 v[110:113], v[134:137], v[192:195], v[110:113]
	v_mfma_f32_16x16x32_bf16 v[106:109], v[138:141], v[188:191], v[106:109]
	v_mfma_f32_16x16x32_bf16 v[106:109], v[142:145], v[192:195], v[106:109]
	v_mfma_f32_16x16x32_bf16 v[94:97], v[130:133], v[196:199], v[94:97]
	v_mfma_f32_16x16x32_bf16 v[94:97], v[134:137], v[200:203], v[94:97]
	v_mfma_f32_16x16x32_bf16 v[90:93], v[138:141], v[196:199], v[90:93]
	v_mfma_f32_16x16x32_bf16 v[90:93], v[142:145], v[200:203], v[90:93]
	v_mfma_f32_16x16x32_bf16 v[78:81], v[130:133], v[204:207], v[78:81]
	v_mfma_f32_16x16x32_bf16 v[78:81], v[134:137], v[208:211], v[78:81]
	v_mfma_f32_16x16x32_bf16 v[74:77], v[138:141], v[204:207], v[74:77]
	v_mfma_f32_16x16x32_bf16 v[74:77], v[142:145], v[208:211], v[74:77]
	s_setprio 0
	s_setprio 1
	v_mfma_f32_16x16x32_bf16 v[118:121], v[146:149], v[176:179], v[118:121]
	v_mfma_f32_16x16x32_bf16 v[118:121], v[150:153], v[180:183], v[118:121]
	v_mfma_f32_16x16x32_bf16 v[114:117], v[154:157], v[176:179], v[114:117]
	v_mfma_f32_16x16x32_bf16 v[114:117], v[172:175], v[180:183], v[114:117]
	v_mfma_f32_16x16x32_bf16 v[102:105], v[146:149], v[188:191], v[102:105]
	v_mfma_f32_16x16x32_bf16 v[102:105], v[150:153], v[192:195], v[102:105]
	v_mfma_f32_16x16x32_bf16 v[98:101], v[154:157], v[188:191], v[98:101]
	v_mfma_f32_16x16x32_bf16 v[98:101], v[172:175], v[192:195], v[98:101]
	v_mfma_f32_16x16x32_bf16 v[86:89], v[146:149], v[196:199], v[86:89]
	v_mfma_f32_16x16x32_bf16 v[86:89], v[150:153], v[200:203], v[86:89]
	v_mfma_f32_16x16x32_bf16 v[82:85], v[154:157], v[196:199], v[82:85]
	v_mfma_f32_16x16x32_bf16 v[82:85], v[172:175], v[200:203], v[82:85]
	v_mfma_f32_16x16x32_bf16 v[70:73], v[146:149], v[204:207], v[70:73]
	v_mfma_f32_16x16x32_bf16 v[70:73], v[150:153], v[208:211], v[70:73]
	v_mfma_f32_16x16x32_bf16 v[66:69], v[154:157], v[204:207], v[66:69]
	v_mfma_f32_16x16x32_bf16 v[66:69], v[172:175], v[208:211], v[66:69]
	s_setprio 0
	s_barrier
	s_add_i32 s28, s30, s11
	v_lshl_add_u64 v[212:213], v[212:213], 0, s[62:63]
	s_mov_b32 m0, s28
	ds_read_b128 v[176:179], v186 offset:49152
	ds_read_b128 v[180:183], v186 offset:50176
	ds_read_b128 v[188:191], v186 offset:51200
	ds_read_b128 v[192:195], v186 offset:52224
	ds_read_b128 v[196:199], v186 offset:53248
	ds_read_b128 v[200:203], v186 offset:54272
	ds_read_b128 v[204:207], v186 offset:55296
	ds_read_b128 v[208:211], v186 offset:56320
	global_load_lds_dwordx4 v[212:213], off
	s_add_i32 m0, s28, 0x2000
	s_add_u32 s28, s68, 0x80080
	v_lshl_add_u64 v[212:213], v[232:233], 0, s[62:63]
	s_addc_u32 s29, s69, 0
	s_add_i32 s30, s31, s11
	global_load_lds_dwordx4 v[212:213], off
	v_lshl_add_u64 v[212:213], s[28:29], 0, v[160:161]
	s_mov_b32 m0, s30
	s_nop 0
	global_load_lds_dwordx4 v[212:213], off
	v_lshl_add_u64 v[212:213], s[28:29], 0, v[164:165]
	s_add_i32 m0, s30, 0x2000
	s_nop 0
	global_load_lds_dwordx4 v[212:213], off
	v_lshl_add_u64 v[212:213], v[234:235], 0, s[62:63]
	s_mov_b32 m0, s18
	s_nop 0
	global_load_lds_dwordx4 v[212:213], off
	v_lshl_add_u64 v[212:213], v[236:237], 0, s[62:63]
	s_mov_b32 m0, s19
	s_nop 0
	global_load_lds_dwordx4 v[212:213], off
	s_waitcnt vmcnt(8)
	s_waitcnt lgkmcnt(0)
	s_barrier
	s_setprio 1
	s_waitcnt lgkmcnt(0)
	v_mfma_f32_16x16x32_bf16 v[62:65], v[130:133], v[176:179], v[62:65]
	v_mfma_f32_16x16x32_bf16 v[62:65], v[134:137], v[180:183], v[62:65]
	v_mfma_f32_16x16x32_bf16 v[58:61], v[138:141], v[176:179], v[58:61]
	v_mfma_f32_16x16x32_bf16 v[58:61], v[142:145], v[180:183], v[58:61]
	v_mfma_f32_16x16x32_bf16 v[46:49], v[130:133], v[188:191], v[46:49]
	v_mfma_f32_16x16x32_bf16 v[46:49], v[134:137], v[192:195], v[46:49]
	v_mfma_f32_16x16x32_bf16 v[42:45], v[138:141], v[188:191], v[42:45]
	v_mfma_f32_16x16x32_bf16 v[42:45], v[142:145], v[192:195], v[42:45]
	v_mfma_f32_16x16x32_bf16 v[30:33], v[130:133], v[196:199], v[30:33]
	v_mfma_f32_16x16x32_bf16 v[30:33], v[134:137], v[200:203], v[30:33]
	v_mfma_f32_16x16x32_bf16 v[26:29], v[138:141], v[196:199], v[26:29]
	v_mfma_f32_16x16x32_bf16 v[26:29], v[142:145], v[200:203], v[26:29]
	v_mfma_f32_16x16x32_bf16 v[14:17], v[130:133], v[204:207], v[14:17]
	v_mfma_f32_16x16x32_bf16 v[14:17], v[134:137], v[208:211], v[14:17]
	v_mfma_f32_16x16x32_bf16 v[10:13], v[138:141], v[204:207], v[10:13]
	v_mfma_f32_16x16x32_bf16 v[10:13], v[142:145], v[208:211], v[10:13]
	s_setprio 0
	s_setprio 1
	v_mfma_f32_16x16x32_bf16 v[54:57], v[146:149], v[176:179], v[54:57]
	v_mfma_f32_16x16x32_bf16 v[54:57], v[150:153], v[180:183], v[54:57]
	v_mfma_f32_16x16x32_bf16 v[50:53], v[154:157], v[176:179], v[50:53]
	v_mfma_f32_16x16x32_bf16 v[50:53], v[172:175], v[180:183], v[50:53]
	v_mfma_f32_16x16x32_bf16 v[38:41], v[146:149], v[188:191], v[38:41]
	v_mfma_f32_16x16x32_bf16 v[38:41], v[150:153], v[192:195], v[38:41]
	v_mfma_f32_16x16x32_bf16 v[34:37], v[154:157], v[188:191], v[34:37]
	v_mfma_f32_16x16x32_bf16 v[34:37], v[172:175], v[192:195], v[34:37]
	v_mfma_f32_16x16x32_bf16 v[22:25], v[146:149], v[196:199], v[22:25]
	v_mfma_f32_16x16x32_bf16 v[22:25], v[150:153], v[200:203], v[22:25]
	v_mfma_f32_16x16x32_bf16 v[18:21], v[154:157], v[196:199], v[18:21]
	v_mfma_f32_16x16x32_bf16 v[18:21], v[172:175], v[200:203], v[18:21]
	v_mfma_f32_16x16x32_bf16 v[6:9], v[146:149], v[204:207], v[6:9]
	v_mfma_f32_16x16x32_bf16 v[6:9], v[150:153], v[208:211], v[6:9]
	v_mfma_f32_16x16x32_bf16 v[2:5], v[154:157], v[204:207], v[2:5]
	v_mfma_f32_16x16x32_bf16 v[2:5], v[172:175], v[208:211], v[2:5]
	s_setprio 0
	s_barrier
	s_add_i32 s27, s27, 2
	s_add_u32 s54, s54, 0x100
	s_addc_u32 s55, s55, 0
	s_add_u32 s25, s25, 0x100
	s_addc_u32 s26, s26, 0
	s_cmp_gt_u32 s27, 29
	s_cbranch_scc0 .LBB0_32
	s_and_b64 vcc, exec, s[2:3]
	s_cbranch_vccz .LBB0_35
	s_barrier

.LBB0_132:
	s_add_u32 s23, s48, 0xfff80080
	s_addc_u32 s24, s49, -1
	s_add_i32 s25, 0, 0x10000
	s_cmp_eq_u32 s22, 28
	s_cselect_b32 s69, s3, s24
	s_cselect_b32 s68, s18, s23
	s_cselect_b32 s51, s1, s21
	s_cselect_b32 s50, s19, s20
	s_add_i32 s23, 0, 0x14000
	v_add_u32_e32 v156, s25, v165
	v_add_u32_e32 v169, s23, v165
	ds_read_b128 v[144:147], v156
	ds_read_b128 v[148:151], v156 offset:1024
	ds_read_b128 v[152:155], v156 offset:2048
	ds_read_b128 v[156:159], v156 offset:3072
	ds_read_b128 v[160:163], v169
	ds_read_b128 v[170:173], v169 offset:1024
	ds_read_b128 v[174:177], v169 offset:2048
	ds_read_b128 v[178:181], v169 offset:3072
	v_lshl_add_u64 v[232:233], s[48:49], 0, v[140:141]
	s_add_i32 m0, s45, 0xc000
	ds_read_b128 v[182:185], v168
	ds_read_b128 v[186:189], v168 offset:1024
	ds_read_b128 v[190:193], v168 offset:2048
	ds_read_b128 v[194:197], v168 offset:3072
	ds_read_b128 v[198:201], v168 offset:4096
	ds_read_b128 v[202:205], v168 offset:5120
	ds_read_b128 v[206:209], v168 offset:6144
	ds_read_b128 v[210:213], v168 offset:7168
	global_load_lds_dwordx4 v[232:233], off
	v_lshl_add_u64 v[232:233], s[48:49], 0, v[142:143]
	s_add_i32 m0, s45, 0xe000
	s_nop 0
	global_load_lds_dwordx4 v[232:233], off
	s_waitcnt vmcnt(8)
	s_waitcnt lgkmcnt(0)
	s_barrier
	s_setprio 1
	s_waitcnt lgkmcnt(0)
	v_mfma_f32_16x16x32_bf16 v[126:129], v[144:147], v[182:185], v[126:129]
	v_mfma_f32_16x16x32_bf16 v[126:129], v[148:151], v[186:189], v[126:129]
	v_mfma_f32_16x16x32_bf16 v[122:125], v[152:155], v[182:185], v[122:125]
	v_mfma_f32_16x16x32_bf16 v[122:125], v[156:159], v[186:189], v[122:125]
	v_mfma_f32_16x16x32_bf16 v[110:113], v[144:147], v[190:193], v[110:113]
	v_mfma_f32_16x16x32_bf16 v[110:113], v[148:151], v[194:197], v[110:113]
	v_mfma_f32_16x16x32_bf16 v[106:109], v[152:155], v[190:193], v[106:109]
	v_mfma_f32_16x16x32_bf16 v[106:109], v[156:159], v[194:197], v[106:109]
	v_mfma_f32_16x16x32_bf16 v[102:105], v[144:147], v[198:201], v[102:105]
	v_mfma_f32_16x16x32_bf16 v[102:105], v[148:151], v[202:205], v[102:105]
	v_mfma_f32_16x16x32_bf16 v[94:97], v[152:155], v[198:201], v[94:97]
	v_mfma_f32_16x16x32_bf16 v[94:97], v[156:159], v[202:205], v[94:97]
	v_mfma_f32_16x16x32_bf16 v[86:89], v[144:147], v[206:209], v[86:89]
	v_mfma_f32_16x16x32_bf16 v[86:89], v[148:151], v[210:213], v[86:89]
	v_mfma_f32_16x16x32_bf16 v[78:81], v[152:155], v[206:209], v[78:81]
	v_mfma_f32_16x16x32_bf16 v[78:81], v[156:159], v[210:213], v[78:81]
	s_setprio 0
	s_setprio 1
	v_mfma_f32_16x16x32_bf16 v[118:121], v[160:163], v[182:185], v[118:121]
	v_mfma_f32_16x16x32_bf16 v[118:121], v[170:173], v[186:189], v[118:121]
	v_mfma_f32_16x16x32_bf16 v[114:117], v[174:177], v[182:185], v[114:117]
	v_mfma_f32_16x16x32_bf16 v[114:117], v[178:181], v[186:189], v[114:117]
	v_mfma_f32_16x16x32_bf16 v[98:101], v[160:163], v[190:193], v[98:101]
	v_mfma_f32_16x16x32_bf16 v[98:101], v[170:173], v[194:197], v[98:101]
	v_mfma_f32_16x16x32_bf16 v[90:93], v[174:177], v[190:193], v[90:93]
	v_mfma_f32_16x16x32_bf16 v[90:93], v[178:181], v[194:197], v[90:93]
	v_mfma_f32_16x16x32_bf16 v[82:85], v[160:163], v[198:201], v[82:85]
	v_mfma_f32_16x16x32_bf16 v[82:85], v[170:173], v[202:205], v[82:85]
	v_mfma_f32_16x16x32_bf16 v[74:77], v[174:177], v[198:201], v[74:77]
	v_mfma_f32_16x16x32_bf16 v[74:77], v[178:181], v[202:205], v[74:77]
	v_mfma_f32_16x16x32_bf16 v[70:73], v[160:163], v[206:209], v[70:73]
	v_mfma_f32_16x16x32_bf16 v[70:73], v[170:173], v[210:213], v[70:73]
	v_mfma_f32_16x16x32_bf16 v[66:69], v[174:177], v[206:209], v[66:69]
	v_mfma_f32_16x16x32_bf16 v[66:69], v[178:181], v[210:213], v[66:69]
	s_setprio 0
	s_barrier
	s_add_i32 s24, s25, s16
	v_lshl_add_u64 v[232:233], s[50:51], 0, v[132:133]
	s_mov_b32 m0, s24
	ds_read_b128 v[182:185], v168 offset:16384
	ds_read_b128 v[186:189], v168 offset:17408
	ds_read_b128 v[190:193], v168 offset:18432
	ds_read_b128 v[194:197], v168 offset:19456
	ds_read_b128 v[198:201], v168 offset:20480
	ds_read_b128 v[202:205], v168 offset:21504
	ds_read_b128 v[206:209], v168 offset:22528
	ds_read_b128 v[210:213], v168 offset:23552
	global_load_lds_dwordx4 v[232:233], off
	s_add_i32 m0, s24, 0x2000
	s_add_u32 s24, s50, 0x80000
	v_lshl_add_u64 v[234:235], s[50:51], 0, v[136:137]
	s_addc_u32 s25, s51, 0
	s_add_i32 s23, s23, s16
	global_load_lds_dwordx4 v[234:235], off
	v_lshl_add_u64 v[236:237], s[24:25], 0, v[132:133]
	s_mov_b32 m0, s23
	v_lshl_add_u64 v[238:239], s[68:69], 0, v[134:135]
	global_load_lds_dwordx4 v[236:237], off
	v_lshl_add_u64 v[236:237], s[24:25], 0, v[136:137]
	s_add_i32 m0, s23, 0x2000
	s_nop 0
	global_load_lds_dwordx4 v[236:237], off
	v_lshl_add_u64 v[236:237], s[68:69], 0, v[130:131]
	s_mov_b32 m0, s45
	s_nop 0
	global_load_lds_dwordx4 v[236:237], off
	s_mov_b32 m0, s57
	s_nop 0
	global_load_lds_dwordx4 v[238:239], off
	s_waitcnt vmcnt(8)
	s_waitcnt lgkmcnt(0)
	s_barrier
	s_setprio 1
	s_waitcnt lgkmcnt(0)
	v_mfma_f32_16x16x32_bf16 v[62:65], v[144:147], v[182:185], v[62:65]
	v_mfma_f32_16x16x32_bf16 v[62:65], v[148:151], v[186:189], v[62:65]
	v_mfma_f32_16x16x32_bf16 v[58:61], v[152:155], v[182:185], v[58:61]
	v_mfma_f32_16x16x32_bf16 v[58:61], v[156:159], v[186:189], v[58:61]
	v_mfma_f32_16x16x32_bf16 v[54:57], v[144:147], v[190:193], v[54:57]
	v_mfma_f32_16x16x32_bf16 v[54:57], v[148:151], v[194:197], v[54:57]
	v_mfma_f32_16x16x32_bf16 v[46:49], v[152:155], v[190:193], v[46:49]
	v_mfma_f32_16x16x32_bf16 v[46:49], v[156:159], v[194:197], v[46:49]
	v_mfma_f32_16x16x32_bf16 v[38:41], v[144:147], v[198:201], v[38:41]
	v_mfma_f32_16x16x32_bf16 v[38:41], v[148:151], v[202:205], v[38:41]
	v_mfma_f32_16x16x32_bf16 v[30:33], v[152:155], v[198:201], v[30:33]
	v_mfma_f32_16x16x32_bf16 v[30:33], v[156:159], v[202:205], v[30:33]
	v_mfma_f32_16x16x32_bf16 v[22:25], v[144:147], v[206:209], v[22:25]
	v_mfma_f32_16x16x32_bf16 v[22:25], v[148:151], v[210:213], v[22:25]
	v_mfma_f32_16x16x32_bf16 v[14:17], v[152:155], v[206:209], v[14:17]
	v_mfma_f32_16x16x32_bf16 v[14:17], v[156:159], v[210:213], v[14:17]
	s_setprio 0
	s_setprio 1
	v_mfma_f32_16x16x32_bf16 v[50:53], v[160:163], v[182:185], v[50:53]
	v_mfma_f32_16x16x32_bf16 v[50:53], v[170:173], v[186:189], v[50:53]
	v_mfma_f32_16x16x32_bf16 v[42:45], v[174:177], v[182:185], v[42:45]
	v_mfma_f32_16x16x32_bf16 v[42:45], v[178:181], v[186:189], v[42:45]
	v_mfma_f32_16x16x32_bf16 v[34:37], v[160:163], v[190:193], v[34:37]
	v_mfma_f32_16x16x32_bf16 v[34:37], v[170:173], v[194:197], v[34:37]
	v_mfma_f32_16x16x32_bf16 v[26:29], v[174:177], v[190:193], v[26:29]
	v_mfma_f32_16x16x32_bf16 v[26:29], v[178:181], v[194:197], v[26:29]
	v_mfma_f32_16x16x32_bf16 v[18:21], v[160:163], v[198:201], v[18:21]
	v_mfma_f32_16x16x32_bf16 v[18:21], v[170:173], v[202:205], v[18:21]
	v_mfma_f32_16x16x32_bf16 v[10:13], v[174:177], v[198:201], v[10:13]
	v_mfma_f32_16x16x32_bf16 v[10:13], v[178:181], v[202:205], v[10:13]
	v_mfma_f32_16x16x32_bf16 v[6:9], v[160:163], v[206:209], v[6:9]
	v_mfma_f32_16x16x32_bf16 v[6:9], v[170:173], v[210:213], v[6:9]
	v_mfma_f32_16x16x32_bf16 v[2:5], v[174:177], v[206:209], v[2:5]
	v_mfma_f32_16x16x32_bf16 v[2:5], v[178:181], v[210:213], v[2:5]
	s_setprio 0
	s_barrier
	s_add_i32 s23, 0, 0x18000
	s_add_i32 s26, 0, 0x1c000
	v_add_u32_e32 v156, s23, v165
	v_add_u32_e32 v169, s26, v165
	ds_read_b128 v[144:147], v156
	ds_read_b128 v[148:151], v156 offset:1024
	ds_read_b128 v[152:155], v156 offset:2048
	ds_read_b128 v[156:159], v156 offset:3072
	ds_read_b128 v[160:163], v169
	ds_read_b128 v[170:173], v169 offset:1024
	ds_read_b128 v[174:177], v169 offset:2048
	ds_read_b128 v[178:181], v169 offset:3072
	s_add_u32 s24, s68, 0x80000
	s_addc_u32 s25, s69, 0
	s_mov_b32 m0, s42
	v_lshl_add_u64 v[240:241], s[24:25], 0, v[130:131]
	ds_read_b128 v[182:185], v168 offset:32768
	ds_read_b128 v[186:189], v168 offset:33792
	ds_read_b128 v[190:193], v168 offset:34816
	ds_read_b128 v[194:197], v168 offset:35840
	ds_read_b128 v[198:201], v168 offset:36864
	ds_read_b128 v[202:205], v168 offset:37888
	ds_read_b128 v[206:209], v168 offset:38912
	ds_read_b128 v[210:213], v168 offset:39936
	global_load_lds_dwordx4 v[240:241], off
	v_lshl_add_u64 v[240:241], s[24:25], 0, v[134:135]
	s_mov_b32 m0, s6
	s_nop 0
	global_load_lds_dwordx4 v[240:241], off
	s_waitcnt vmcnt(8)
	s_waitcnt lgkmcnt(0)
	s_barrier
	s_setprio 1
	s_waitcnt lgkmcnt(0)
	v_mfma_f32_16x16x32_bf16 v[126:129], v[144:147], v[182:185], v[126:129]
	v_mfma_f32_16x16x32_bf16 v[126:129], v[148:151], v[186:189], v[126:129]
	v_mfma_f32_16x16x32_bf16 v[122:125], v[152:155], v[182:185], v[122:125]
	v_mfma_f32_16x16x32_bf16 v[122:125], v[156:159], v[186:189], v[122:125]
	v_mfma_f32_16x16x32_bf16 v[110:113], v[144:147], v[190:193], v[110:113]
	v_mfma_f32_16x16x32_bf16 v[110:113], v[148:151], v[194:197], v[110:113]
	v_mfma_f32_16x16x32_bf16 v[106:109], v[152:155], v[190:193], v[106:109]
	v_mfma_f32_16x16x32_bf16 v[106:109], v[156:159], v[194:197], v[106:109]
	v_mfma_f32_16x16x32_bf16 v[102:105], v[144:147], v[198:201], v[102:105]
	v_mfma_f32_16x16x32_bf16 v[102:105], v[148:151], v[202:205], v[102:105]
	v_mfma_f32_16x16x32_bf16 v[94:97], v[152:155], v[198:201], v[94:97]
	v_mfma_f32_16x16x32_bf16 v[94:97], v[156:159], v[202:205], v[94:97]
	v_mfma_f32_16x16x32_bf16 v[86:89], v[144:147], v[206:209], v[86:89]
	v_mfma_f32_16x16x32_bf16 v[86:89], v[148:151], v[210:213], v[86:89]
	v_mfma_f32_16x16x32_bf16 v[78:81], v[152:155], v[206:209], v[78:81]
	v_mfma_f32_16x16x32_bf16 v[78:81], v[156:159], v[210:213], v[78:81]
	s_setprio 0
	s_setprio 1
	v_mfma_f32_16x16x32_bf16 v[118:121], v[160:163], v[182:185], v[118:121]
	v_mfma_f32_16x16x32_bf16 v[118:121], v[170:173], v[186:189], v[118:121]
	v_mfma_f32_16x16x32_bf16 v[114:117], v[174:177], v[182:185], v[114:117]
	v_mfma_f32_16x16x32_bf16 v[114:117], v[178:181], v[186:189], v[114:117]
	v_mfma_f32_16x16x32_bf16 v[98:101], v[160:163], v[190:193], v[98:101]
	v_mfma_f32_16x16x32_bf16 v[98:101], v[170:173], v[194:197], v[98:101]
	v_mfma_f32_16x16x32_bf16 v[90:93], v[174:177], v[190:193], v[90:93]
	v_mfma_f32_16x16x32_bf16 v[90:93], v[178:181], v[194:197], v[90:93]
	v_mfma_f32_16x16x32_bf16 v[82:85], v[160:163], v[198:201], v[82:85]
	v_mfma_f32_16x16x32_bf16 v[82:85], v[170:173], v[202:205], v[82:85]
	v_mfma_f32_16x16x32_bf16 v[74:77], v[174:177], v[198:201], v[74:77]
	v_mfma_f32_16x16x32_bf16 v[74:77], v[178:181], v[202:205], v[74:77]
	v_mfma_f32_16x16x32_bf16 v[70:73], v[160:163], v[206:209], v[70:73]
	v_mfma_f32_16x16x32_bf16 v[70:73], v[170:173], v[210:213], v[70:73]
	v_mfma_f32_16x16x32_bf16 v[66:69], v[174:177], v[206:209], v[66:69]
	v_mfma_f32_16x16x32_bf16 v[66:69], v[178:181], v[210:213], v[66:69]
	s_setprio 0
	s_barrier
	s_add_i32 s23, s23, s16
	v_lshl_add_u64 v[232:233], v[232:233], 0, s[62:63]
	s_mov_b32 m0, s23
	ds_read_b128 v[182:185], v168 offset:49152
	ds_read_b128 v[186:189], v168 offset:50176
	ds_read_b128 v[190:193], v168 offset:51200
	ds_read_b128 v[194:197], v168 offset:52224
	ds_read_b128 v[198:201], v168 offset:53248
	ds_read_b128 v[202:205], v168 offset:54272
	ds_read_b128 v[206:209], v168 offset:55296
	ds_read_b128 v[210:213], v168 offset:56320
	global_load_lds_dwordx4 v[232:233], off
	s_add_i32 m0, s23, 0x2000
	s_add_u32 s24, s50, 0x80080
	v_lshl_add_u64 v[232:233], v[234:235], 0, s[62:63]
	s_addc_u32 s25, s51, 0
	s_add_i32 s23, s26, s16
	global_load_lds_dwordx4 v[232:233], off
	v_lshl_add_u64 v[232:233], s[24:25], 0, v[132:133]
	s_mov_b32 m0, s23
	s_nop 0
	global_load_lds_dwordx4 v[232:233], off
	v_lshl_add_u64 v[232:233], s[24:25], 0, v[136:137]
	s_add_i32 m0, s23, 0x2000
	s_nop 0
	global_load_lds_dwordx4 v[232:233], off
	v_lshl_add_u64 v[232:233], v[236:237], 0, s[62:63]
	s_mov_b32 m0, s76
	s_nop 0
	global_load_lds_dwordx4 v[232:233], off
	v_lshl_add_u64 v[232:233], v[238:239], 0, s[62:63]
	s_mov_b32 m0, s77
	s_nop 0
	global_load_lds_dwordx4 v[232:233], off
	s_waitcnt vmcnt(8)
	s_waitcnt lgkmcnt(0)
	s_barrier
	s_setprio 1
	s_waitcnt lgkmcnt(0)
	v_mfma_f32_16x16x32_bf16 v[62:65], v[144:147], v[182:185], v[62:65]
	v_mfma_f32_16x16x32_bf16 v[62:65], v[148:151], v[186:189], v[62:65]
	v_mfma_f32_16x16x32_bf16 v[58:61], v[152:155], v[182:185], v[58:61]
	v_mfma_f32_16x16x32_bf16 v[58:61], v[156:159], v[186:189], v[58:61]
	v_mfma_f32_16x16x32_bf16 v[54:57], v[144:147], v[190:193], v[54:57]
	v_mfma_f32_16x16x32_bf16 v[54:57], v[148:151], v[194:197], v[54:57]
	v_mfma_f32_16x16x32_bf16 v[46:49], v[152:155], v[190:193], v[46:49]
	v_mfma_f32_16x16x32_bf16 v[46:49], v[156:159], v[194:197], v[46:49]
	v_mfma_f32_16x16x32_bf16 v[38:41], v[144:147], v[198:201], v[38:41]
	v_mfma_f32_16x16x32_bf16 v[38:41], v[148:151], v[202:205], v[38:41]
	v_mfma_f32_16x16x32_bf16 v[30:33], v[152:155], v[198:201], v[30:33]
	v_mfma_f32_16x16x32_bf16 v[30:33], v[156:159], v[202:205], v[30:33]
	v_mfma_f32_16x16x32_bf16 v[22:25], v[144:147], v[206:209], v[22:25]
	v_mfma_f32_16x16x32_bf16 v[22:25], v[148:151], v[210:213], v[22:25]
	v_mfma_f32_16x16x32_bf16 v[14:17], v[152:155], v[206:209], v[14:17]
	v_mfma_f32_16x16x32_bf16 v[14:17], v[156:159], v[210:213], v[14:17]
	s_setprio 0
	s_setprio 1
	v_mfma_f32_16x16x32_bf16 v[50:53], v[160:163], v[182:185], v[50:53]
	v_mfma_f32_16x16x32_bf16 v[50:53], v[170:173], v[186:189], v[50:53]
	v_mfma_f32_16x16x32_bf16 v[42:45], v[174:177], v[182:185], v[42:45]
	v_mfma_f32_16x16x32_bf16 v[42:45], v[178:181], v[186:189], v[42:45]
	v_mfma_f32_16x16x32_bf16 v[34:37], v[160:163], v[190:193], v[34:37]
	v_mfma_f32_16x16x32_bf16 v[34:37], v[170:173], v[194:197], v[34:37]
	v_mfma_f32_16x16x32_bf16 v[26:29], v[174:177], v[190:193], v[26:29]
	v_mfma_f32_16x16x32_bf16 v[26:29], v[178:181], v[194:197], v[26:29]
	v_mfma_f32_16x16x32_bf16 v[18:21], v[160:163], v[198:201], v[18:21]
	v_mfma_f32_16x16x32_bf16 v[18:21], v[170:173], v[202:205], v[18:21]
	v_mfma_f32_16x16x32_bf16 v[10:13], v[174:177], v[198:201], v[10:13]
	v_mfma_f32_16x16x32_bf16 v[10:13], v[178:181], v[202:205], v[10:13]
	v_mfma_f32_16x16x32_bf16 v[6:9], v[160:163], v[206:209], v[6:9]
	v_mfma_f32_16x16x32_bf16 v[6:9], v[170:173], v[210:213], v[6:9]
	v_mfma_f32_16x16x32_bf16 v[2:5], v[174:177], v[206:209], v[2:5]
	v_mfma_f32_16x16x32_bf16 v[2:5], v[178:181], v[210:213], v[2:5]
	s_setprio 0
	s_barrier
	s_add_i32 s22, s22, 2
	s_add_u32 s48, s48, 0x100
	s_addc_u32 s49, s49, 0
	s_add_u32 s20, s20, 0x100
	s_addc_u32 s21, s21, 0
	s_cmp_gt_u32 s22, 29
	s_cbranch_scc0 .LBB0_132
	s_and_b64 vcc, exec, s[10:11]
	s_cbranch_vccz .LBB0_135
	s_barrier

.LBB0_238:
	s_add_u32 s10, s12, 0x100
	s_addc_u32 s11, s13, 0
	s_add_i32 s23, 0, 0x10000
	s_cmpk_eq_i32 s22, 0x52
	s_cselect_b32 vcc_hi, s47, s11
	s_cselect_b32 vcc_lo, s46, s10
	s_cselect_b32 s51, s49, s21
	s_cselect_b32 s50, s48, s20
	s_add_i32 s24, 0, 0x14000
	v_add_u32_e32 v142, s23, v194
	v_add_u32_e32 v158, s24, v194
	ds_read_b128 v[122:125], v142
	ds_read_b128 v[126:129], v142 offset:1024
	ds_read_b128 v[138:141], v142 offset:2048
	ds_read_b128 v[142:145], v142 offset:3072
	ds_read_b128 v[146:149], v158
	ds_read_b128 v[150:153], v158 offset:1024
	ds_read_b128 v[154:157], v158 offset:2048
	ds_read_b128 v[158:161], v158 offset:3072
	v_lshl_add_u64 v[212:213], s[12:13], 0, v[170:171]
	s_add_i32 m0, s57, 0xc000
	ds_read_b128 v[174:177], v198
	ds_read_b128 v[178:181], v198 offset:1024
	ds_read_b128 v[182:185], v198 offset:2048
	ds_read_b128 v[186:189], v198 offset:3072
	ds_read_b128 v[190:193], v198 offset:4096
	ds_read_b128 v[200:203], v198 offset:5120
	ds_read_b128 v[204:207], v198 offset:6144
	ds_read_b128 v[208:211], v198 offset:7168
	global_load_lds_dwordx4 v[212:213], off
	v_lshl_add_u64 v[212:213], s[12:13], 0, v[172:173]
	s_add_i32 m0, s57, 0xe000
	s_nop 0
	global_load_lds_dwordx4 v[212:213], off
	s_waitcnt vmcnt(8)
	s_waitcnt lgkmcnt(0)
	s_barrier
	s_setprio 1
	s_waitcnt lgkmcnt(0)
	v_mfma_f32_16x16x32_bf16 v[134:137], v[122:125], v[174:177], v[134:137]
	v_mfma_f32_16x16x32_bf16 v[134:137], v[126:129], v[178:181], v[134:137]
	v_mfma_f32_16x16x32_bf16 v[130:133], v[138:141], v[174:177], v[130:133]
	v_mfma_f32_16x16x32_bf16 v[130:133], v[142:145], v[178:181], v[130:133]
	v_mfma_f32_16x16x32_bf16 v[110:113], v[122:125], v[182:185], v[110:113]
	v_mfma_f32_16x16x32_bf16 v[110:113], v[126:129], v[186:189], v[110:113]
	v_mfma_f32_16x16x32_bf16 v[106:109], v[138:141], v[182:185], v[106:109]
	v_mfma_f32_16x16x32_bf16 v[106:109], v[142:145], v[186:189], v[106:109]
	v_mfma_f32_16x16x32_bf16 v[94:97], v[122:125], v[190:193], v[94:97]
	v_mfma_f32_16x16x32_bf16 v[94:97], v[126:129], v[200:203], v[94:97]
	v_mfma_f32_16x16x32_bf16 v[90:93], v[138:141], v[190:193], v[90:93]
	v_mfma_f32_16x16x32_bf16 v[90:93], v[142:145], v[200:203], v[90:93]
	v_mfma_f32_16x16x32_bf16 v[78:81], v[122:125], v[204:207], v[78:81]
	v_mfma_f32_16x16x32_bf16 v[78:81], v[126:129], v[208:211], v[78:81]
	v_mfma_f32_16x16x32_bf16 v[74:77], v[138:141], v[204:207], v[74:77]
	v_mfma_f32_16x16x32_bf16 v[74:77], v[142:145], v[208:211], v[74:77]
	s_setprio 0
	s_setprio 1
	v_mfma_f32_16x16x32_bf16 v[118:121], v[146:149], v[174:177], v[118:121]
	v_mfma_f32_16x16x32_bf16 v[118:121], v[150:153], v[178:181], v[118:121]
	v_mfma_f32_16x16x32_bf16 v[114:117], v[154:157], v[174:177], v[114:117]
	v_mfma_f32_16x16x32_bf16 v[114:117], v[158:161], v[178:181], v[114:117]
	v_mfma_f32_16x16x32_bf16 v[102:105], v[146:149], v[182:185], v[102:105]
	v_mfma_f32_16x16x32_bf16 v[102:105], v[150:153], v[186:189], v[102:105]
	v_mfma_f32_16x16x32_bf16 v[98:101], v[154:157], v[182:185], v[98:101]
	v_mfma_f32_16x16x32_bf16 v[98:101], v[158:161], v[186:189], v[98:101]
	v_mfma_f32_16x16x32_bf16 v[86:89], v[146:149], v[190:193], v[86:89]
	v_mfma_f32_16x16x32_bf16 v[86:89], v[150:153], v[200:203], v[86:89]
	v_mfma_f32_16x16x32_bf16 v[82:85], v[154:157], v[190:193], v[82:85]
	v_mfma_f32_16x16x32_bf16 v[82:85], v[158:161], v[200:203], v[82:85]
	v_mfma_f32_16x16x32_bf16 v[70:73], v[146:149], v[204:207], v[70:73]
	v_mfma_f32_16x16x32_bf16 v[70:73], v[150:153], v[208:211], v[70:73]
	v_mfma_f32_16x16x32_bf16 v[66:69], v[154:157], v[204:207], v[66:69]
	v_mfma_f32_16x16x32_bf16 v[66:69], v[158:161], v[208:211], v[66:69]
	s_setprio 0
	s_barrier
	s_add_i32 s12, s23, s42
	v_lshl_add_u64 v[212:213], s[50:51], 0, v[164:165]
	s_mov_b32 m0, s12
	ds_read_b128 v[174:177], v198 offset:16384
	ds_read_b128 v[178:181], v198 offset:17408
	ds_read_b128 v[182:185], v198 offset:18432
	ds_read_b128 v[186:189], v198 offset:19456
	ds_read_b128 v[190:193], v198 offset:20480
	ds_read_b128 v[200:203], v198 offset:21504
	ds_read_b128 v[204:207], v198 offset:22528
	ds_read_b128 v[208:211], v198 offset:23552
	global_load_lds_dwordx4 v[212:213], off
	s_add_i32 m0, s12, 0x2000
	s_add_u32 s12, s50, 0x158000
	v_lshl_add_u64 v[232:233], s[50:51], 0, v[168:169]
	s_addc_u32 s13, s51, 0
	s_add_i32 s23, s24, s42
	global_load_lds_dwordx4 v[232:233], off
	v_lshl_add_u64 v[234:235], s[12:13], 0, v[164:165]
	s_mov_b32 m0, s23
	v_lshl_add_u64 v[236:237], vcc, 0, v[166:167]
	global_load_lds_dwordx4 v[234:235], off
	v_lshl_add_u64 v[234:235], s[12:13], 0, v[168:169]
	s_add_i32 m0, s23, 0x2000
	s_nop 0
	global_load_lds_dwordx4 v[234:235], off
	v_lshl_add_u64 v[234:235], vcc, 0, v[162:163]
	s_mov_b32 m0, s57
	s_nop 0
	global_load_lds_dwordx4 v[234:235], off
	s_mov_b32 m0, s58
	s_nop 0
	global_load_lds_dwordx4 v[236:237], off
	s_waitcnt vmcnt(8)
	s_waitcnt lgkmcnt(0)
	s_barrier
	s_setprio 1
	s_waitcnt lgkmcnt(0)
	v_mfma_f32_16x16x32_bf16 v[62:65], v[122:125], v[174:177], v[62:65]
	v_mfma_f32_16x16x32_bf16 v[62:65], v[126:129], v[178:181], v[62:65]
	v_mfma_f32_16x16x32_bf16 v[58:61], v[138:141], v[174:177], v[58:61]
	v_mfma_f32_16x16x32_bf16 v[58:61], v[142:145], v[178:181], v[58:61]
	v_mfma_f32_16x16x32_bf16 v[46:49], v[122:125], v[182:185], v[46:49]
	v_mfma_f32_16x16x32_bf16 v[46:49], v[126:129], v[186:189], v[46:49]
	v_mfma_f32_16x16x32_bf16 v[42:45], v[138:141], v[182:185], v[42:45]
	v_mfma_f32_16x16x32_bf16 v[42:45], v[142:145], v[186:189], v[42:45]
	v_mfma_f32_16x16x32_bf16 v[30:33], v[122:125], v[190:193], v[30:33]
	v_mfma_f32_16x16x32_bf16 v[30:33], v[126:129], v[200:203], v[30:33]
	v_mfma_f32_16x16x32_bf16 v[26:29], v[138:141], v[190:193], v[26:29]
	v_mfma_f32_16x16x32_bf16 v[26:29], v[142:145], v[200:203], v[26:29]
	v_mfma_f32_16x16x32_bf16 v[14:17], v[122:125], v[204:207], v[14:17]
	v_mfma_f32_16x16x32_bf16 v[14:17], v[126:129], v[208:211], v[14:17]
	v_mfma_f32_16x16x32_bf16 v[10:13], v[138:141], v[204:207], v[10:13]
	v_mfma_f32_16x16x32_bf16 v[10:13], v[142:145], v[208:211], v[10:13]
	s_setprio 0
	s_setprio 1
	v_mfma_f32_16x16x32_bf16 v[54:57], v[146:149], v[174:177], v[54:57]
	v_mfma_f32_16x16x32_bf16 v[54:57], v[150:153], v[178:181], v[54:57]
	v_mfma_f32_16x16x32_bf16 v[50:53], v[154:157], v[174:177], v[50:53]
	v_mfma_f32_16x16x32_bf16 v[50:53], v[158:161], v[178:181], v[50:53]
	v_mfma_f32_16x16x32_bf16 v[38:41], v[146:149], v[182:185], v[38:41]
	v_mfma_f32_16x16x32_bf16 v[38:41], v[150:153], v[186:189], v[38:41]
	v_mfma_f32_16x16x32_bf16 v[34:37], v[154:157], v[182:185], v[34:37]
	v_mfma_f32_16x16x32_bf16 v[34:37], v[158:161], v[186:189], v[34:37]
	v_mfma_f32_16x16x32_bf16 v[22:25], v[146:149], v[190:193], v[22:25]
	v_mfma_f32_16x16x32_bf16 v[22:25], v[150:153], v[200:203], v[22:25]
	v_mfma_f32_16x16x32_bf16 v[18:21], v[154:157], v[190:193], v[18:21]
	v_mfma_f32_16x16x32_bf16 v[18:21], v[158:161], v[200:203], v[18:21]
	v_mfma_f32_16x16x32_bf16 v[6:9], v[146:149], v[204:207], v[6:9]
	v_mfma_f32_16x16x32_bf16 v[6:9], v[150:153], v[208:211], v[6:9]
	v_mfma_f32_16x16x32_bf16 v[2:5], v[154:157], v[204:207], v[2:5]
	v_mfma_f32_16x16x32_bf16 v[2:5], v[158:161], v[208:211], v[2:5]
	s_setprio 0
	s_barrier
	s_add_i32 s23, 0, 0x18000
	s_add_i32 s24, 0, 0x1c000
	v_add_u32_e32 v142, s23, v194
	v_add_u32_e32 v158, s24, v194
	ds_read_b128 v[122:125], v142
	ds_read_b128 v[126:129], v142 offset:1024
	ds_read_b128 v[138:141], v142 offset:2048
	ds_read_b128 v[142:145], v142 offset:3072
	ds_read_b128 v[146:149], v158
	ds_read_b128 v[150:153], v158 offset:1024
	ds_read_b128 v[154:157], v158 offset:2048
	ds_read_b128 v[158:161], v158 offset:3072
	s_add_u32 s12, vcc_lo, 0x158000
	s_addc_u32 s13, vcc_hi, 0
	s_mov_b32 m0, s67
	v_lshl_add_u64 v[238:239], s[12:13], 0, v[162:163]
	ds_read_b128 v[174:177], v198 offset:32768
	ds_read_b128 v[178:181], v198 offset:33792
	ds_read_b128 v[182:185], v198 offset:34816
	ds_read_b128 v[186:189], v198 offset:35840
	ds_read_b128 v[190:193], v198 offset:36864
	ds_read_b128 v[200:203], v198 offset:37888
	ds_read_b128 v[204:207], v198 offset:38912
	ds_read_b128 v[208:211], v198 offset:39936
	global_load_lds_dwordx4 v[238:239], off
	v_lshl_add_u64 v[238:239], s[12:13], 0, v[166:167]
	s_mov_b32 m0, s76
	s_nop 0
	global_load_lds_dwordx4 v[238:239], off
	s_waitcnt vmcnt(8)
	s_waitcnt lgkmcnt(0)
	s_barrier
	s_setprio 1
	s_waitcnt lgkmcnt(0)
	v_mfma_f32_16x16x32_bf16 v[134:137], v[122:125], v[174:177], v[134:137]
	v_mfma_f32_16x16x32_bf16 v[134:137], v[126:129], v[178:181], v[134:137]
	v_mfma_f32_16x16x32_bf16 v[130:133], v[138:141], v[174:177], v[130:133]
	v_mfma_f32_16x16x32_bf16 v[130:133], v[142:145], v[178:181], v[130:133]
	v_mfma_f32_16x16x32_bf16 v[110:113], v[122:125], v[182:185], v[110:113]
	v_mfma_f32_16x16x32_bf16 v[110:113], v[126:129], v[186:189], v[110:113]
	v_mfma_f32_16x16x32_bf16 v[106:109], v[138:141], v[182:185], v[106:109]
	v_mfma_f32_16x16x32_bf16 v[106:109], v[142:145], v[186:189], v[106:109]
	v_mfma_f32_16x16x32_bf16 v[94:97], v[122:125], v[190:193], v[94:97]
	v_mfma_f32_16x16x32_bf16 v[94:97], v[126:129], v[200:203], v[94:97]
	v_mfma_f32_16x16x32_bf16 v[90:93], v[138:141], v[190:193], v[90:93]
	v_mfma_f32_16x16x32_bf16 v[90:93], v[142:145], v[200:203], v[90:93]
	v_mfma_f32_16x16x32_bf16 v[78:81], v[122:125], v[204:207], v[78:81]
	v_mfma_f32_16x16x32_bf16 v[78:81], v[126:129], v[208:211], v[78:81]
	v_mfma_f32_16x16x32_bf16 v[74:77], v[138:141], v[204:207], v[74:77]
	v_mfma_f32_16x16x32_bf16 v[74:77], v[142:145], v[208:211], v[74:77]
	s_setprio 0
	s_setprio 1
	v_mfma_f32_16x16x32_bf16 v[118:121], v[146:149], v[174:177], v[118:121]
	v_mfma_f32_16x16x32_bf16 v[118:121], v[150:153], v[178:181], v[118:121]
	v_mfma_f32_16x16x32_bf16 v[114:117], v[154:157], v[174:177], v[114:117]
	v_mfma_f32_16x16x32_bf16 v[114:117], v[158:161], v[178:181], v[114:117]
	v_mfma_f32_16x16x32_bf16 v[102:105], v[146:149], v[182:185], v[102:105]
	v_mfma_f32_16x16x32_bf16 v[102:105], v[150:153], v[186:189], v[102:105]
	v_mfma_f32_16x16x32_bf16 v[98:101], v[154:157], v[182:185], v[98:101]
	v_mfma_f32_16x16x32_bf16 v[98:101], v[158:161], v[186:189], v[98:101]
	v_mfma_f32_16x16x32_bf16 v[86:89], v[146:149], v[190:193], v[86:89]
	v_mfma_f32_16x16x32_bf16 v[86:89], v[150:153], v[200:203], v[86:89]
	v_mfma_f32_16x16x32_bf16 v[82:85], v[154:157], v[190:193], v[82:85]
	v_mfma_f32_16x16x32_bf16 v[82:85], v[158:161], v[200:203], v[82:85]
	v_mfma_f32_16x16x32_bf16 v[70:73], v[146:149], v[204:207], v[70:73]
	v_mfma_f32_16x16x32_bf16 v[70:73], v[150:153], v[208:211], v[70:73]
	v_mfma_f32_16x16x32_bf16 v[66:69], v[154:157], v[204:207], v[66:69]
	v_mfma_f32_16x16x32_bf16 v[66:69], v[158:161], v[208:211], v[66:69]
	s_setprio 0
	s_barrier
	s_add_i32 s12, s23, s42
	v_lshl_add_u64 v[212:213], v[212:213], 0, s[62:63]
	s_mov_b32 m0, s12
	ds_read_b128 v[174:177], v198 offset:49152
	ds_read_b128 v[178:181], v198 offset:50176
	ds_read_b128 v[182:185], v198 offset:51200
	ds_read_b128 v[186:189], v198 offset:52224
	ds_read_b128 v[190:193], v198 offset:53248
	ds_read_b128 v[200:203], v198 offset:54272
	ds_read_b128 v[204:207], v198 offset:55296
	ds_read_b128 v[208:211], v198 offset:56320
	global_load_lds_dwordx4 v[212:213], off
	s_add_i32 m0, s12, 0x2000
	s_add_u32 s12, s50, 0x158080
	v_lshl_add_u64 v[212:213], v[232:233], 0, s[62:63]
	s_addc_u32 s13, s51, 0
	s_add_i32 s23, s24, s42
	global_load_lds_dwordx4 v[212:213], off
	v_lshl_add_u64 v[212:213], s[12:13], 0, v[164:165]
	s_mov_b32 m0, s23
	s_nop 0
	global_load_lds_dwordx4 v[212:213], off
	v_lshl_add_u64 v[212:213], s[12:13], 0, v[168:169]
	s_add_i32 m0, s23, 0x2000
	s_nop 0
	global_load_lds_dwordx4 v[212:213], off
	v_lshl_add_u64 v[212:213], v[234:235], 0, s[62:63]
	s_mov_b32 m0, s1
	s_nop 0
	global_load_lds_dwordx4 v[212:213], off
	v_lshl_add_u64 v[212:213], v[236:237], 0, s[62:63]
	s_mov_b32 m0, s52
	s_nop 0
	global_load_lds_dwordx4 v[212:213], off
	s_waitcnt vmcnt(8)
	s_waitcnt lgkmcnt(0)
	s_barrier
	s_setprio 1
	s_waitcnt lgkmcnt(0)
	v_mfma_f32_16x16x32_bf16 v[62:65], v[122:125], v[174:177], v[62:65]
	v_mfma_f32_16x16x32_bf16 v[62:65], v[126:129], v[178:181], v[62:65]
	v_mfma_f32_16x16x32_bf16 v[58:61], v[138:141], v[174:177], v[58:61]
	v_mfma_f32_16x16x32_bf16 v[58:61], v[142:145], v[178:181], v[58:61]
	v_mfma_f32_16x16x32_bf16 v[46:49], v[122:125], v[182:185], v[46:49]
	v_mfma_f32_16x16x32_bf16 v[46:49], v[126:129], v[186:189], v[46:49]
	v_mfma_f32_16x16x32_bf16 v[42:45], v[138:141], v[182:185], v[42:45]
	v_mfma_f32_16x16x32_bf16 v[42:45], v[142:145], v[186:189], v[42:45]
	v_mfma_f32_16x16x32_bf16 v[30:33], v[122:125], v[190:193], v[30:33]
	v_mfma_f32_16x16x32_bf16 v[30:33], v[126:129], v[200:203], v[30:33]
	v_mfma_f32_16x16x32_bf16 v[26:29], v[138:141], v[190:193], v[26:29]
	v_mfma_f32_16x16x32_bf16 v[26:29], v[142:145], v[200:203], v[26:29]
	v_mfma_f32_16x16x32_bf16 v[14:17], v[122:125], v[204:207], v[14:17]
	v_mfma_f32_16x16x32_bf16 v[14:17], v[126:129], v[208:211], v[14:17]
	v_mfma_f32_16x16x32_bf16 v[10:13], v[138:141], v[204:207], v[10:13]
	v_mfma_f32_16x16x32_bf16 v[10:13], v[142:145], v[208:211], v[10:13]
	s_setprio 0
	s_setprio 1
	v_mfma_f32_16x16x32_bf16 v[54:57], v[146:149], v[174:177], v[54:57]
	v_mfma_f32_16x16x32_bf16 v[54:57], v[150:153], v[178:181], v[54:57]
	v_mfma_f32_16x16x32_bf16 v[50:53], v[154:157], v[174:177], v[50:53]
	v_mfma_f32_16x16x32_bf16 v[50:53], v[158:161], v[178:181], v[50:53]
	v_mfma_f32_16x16x32_bf16 v[38:41], v[146:149], v[182:185], v[38:41]
	v_mfma_f32_16x16x32_bf16 v[38:41], v[150:153], v[186:189], v[38:41]
	v_mfma_f32_16x16x32_bf16 v[34:37], v[154:157], v[182:185], v[34:37]
	v_mfma_f32_16x16x32_bf16 v[34:37], v[158:161], v[186:189], v[34:37]
	v_mfma_f32_16x16x32_bf16 v[22:25], v[146:149], v[190:193], v[22:25]
	v_mfma_f32_16x16x32_bf16 v[22:25], v[150:153], v[200:203], v[22:25]
	v_mfma_f32_16x16x32_bf16 v[18:21], v[154:157], v[190:193], v[18:21]
	v_mfma_f32_16x16x32_bf16 v[18:21], v[158:161], v[200:203], v[18:21]
	v_mfma_f32_16x16x32_bf16 v[6:9], v[146:149], v[204:207], v[6:9]
	v_mfma_f32_16x16x32_bf16 v[6:9], v[150:153], v[208:211], v[6:9]
	v_mfma_f32_16x16x32_bf16 v[2:5], v[154:157], v[204:207], v[2:5]
	v_mfma_f32_16x16x32_bf16 v[2:5], v[158:161], v[208:211], v[2:5]
	s_setprio 0
	s_barrier
	s_add_i32 s22, s22, 2
	s_add_u32 s20, s20, 0x100
	s_addc_u32 s21, s21, 0
	s_cmpk_gt_u32 s22, 0x53
	s_mov_b64 s[12:13], s[10:11]
	s_cbranch_scc0 .LBB0_238
	s_and_b64 vcc, exec, s[2:3]
	s_cbranch_vccz .LBB0_241
	s_barrier

.LBB0_340:
	s_add_u32 s22, s46, 0xfff80080
	s_addc_u32 s23, s47, -1
	s_add_i32 s24, 0, 0x10000
	s_cmp_eq_u32 s21, 28
	s_cselect_b32 s51, s1, s23
	s_cselect_b32 s50, s13, s22
	v_add_u32_e32 v148, s24, v152
	s_cselect_b32 s49, s11, s20
	s_cselect_b32 s48, s18, s19
	s_add_i32 s25, 0, 0x14000
	ds_read_b128 v[144:147], v148
	ds_read_b128 v[156:159], v148 offset:1024
	ds_read_b128 v[160:163], v148 offset:2048
	ds_read_b128 v[164:167], v148 offset:3072
	v_add_u32_e32 v148, s25, v152
	ds_read_b128 v[168:171], v148
	ds_read_b128 v[172:175], v148 offset:1024
	ds_read_b128 v[176:179], v148 offset:2048
	ds_read_b128 v[180:183], v148 offset:3072
	v_lshl_add_u64 v[148:149], s[46:47], 0, v[140:141]
	s_add_i32 m0, s3, 0xc000
	ds_read_b128 v[184:187], v154
	ds_read_b128 v[188:191], v154 offset:1024
	ds_read_b128 v[192:195], v154 offset:2048
	ds_read_b128 v[196:199], v154 offset:3072
	ds_read_b128 v[200:203], v154 offset:4096
	ds_read_b128 v[204:207], v154 offset:5120
	ds_read_b128 v[208:211], v154 offset:6144
	ds_read_b128 v[232:235], v154 offset:7168
	global_load_lds_dwordx4 v[148:149], off
	v_lshl_add_u64 v[148:149], s[46:47], 0, v[142:143]
	s_add_i32 m0, s3, 0xe000
	s_nop 0
	global_load_lds_dwordx4 v[148:149], off
	s_waitcnt vmcnt(8)
	s_waitcnt lgkmcnt(0)
	s_barrier
	s_setprio 1
	s_waitcnt lgkmcnt(0)
	v_mfma_f32_16x16x32_bf16 v[126:129], v[144:147], v[184:187], v[126:129]
	v_mfma_f32_16x16x32_bf16 v[126:129], v[156:159], v[188:191], v[126:129]
	v_mfma_f32_16x16x32_bf16 v[122:125], v[160:163], v[184:187], v[122:125]
	v_mfma_f32_16x16x32_bf16 v[122:125], v[164:167], v[188:191], v[122:125]
	v_mfma_f32_16x16x32_bf16 v[110:113], v[144:147], v[192:195], v[110:113]
	v_mfma_f32_16x16x32_bf16 v[110:113], v[156:159], v[196:199], v[110:113]
	v_mfma_f32_16x16x32_bf16 v[106:109], v[160:163], v[192:195], v[106:109]
	v_mfma_f32_16x16x32_bf16 v[106:109], v[164:167], v[196:199], v[106:109]
	v_mfma_f32_16x16x32_bf16 v[94:97], v[144:147], v[200:203], v[94:97]
	v_mfma_f32_16x16x32_bf16 v[94:97], v[156:159], v[204:207], v[94:97]
	v_mfma_f32_16x16x32_bf16 v[90:93], v[160:163], v[200:203], v[90:93]
	v_mfma_f32_16x16x32_bf16 v[90:93], v[164:167], v[204:207], v[90:93]
	v_mfma_f32_16x16x32_bf16 v[78:81], v[144:147], v[208:211], v[78:81]
	v_mfma_f32_16x16x32_bf16 v[78:81], v[156:159], v[232:235], v[78:81]
	v_mfma_f32_16x16x32_bf16 v[74:77], v[160:163], v[208:211], v[74:77]
	v_mfma_f32_16x16x32_bf16 v[74:77], v[164:167], v[232:235], v[74:77]
	s_setprio 0
	s_setprio 1
	v_mfma_f32_16x16x32_bf16 v[118:121], v[168:171], v[184:187], v[118:121]
	v_mfma_f32_16x16x32_bf16 v[118:121], v[172:175], v[188:191], v[118:121]
	v_mfma_f32_16x16x32_bf16 v[114:117], v[176:179], v[184:187], v[114:117]
	v_mfma_f32_16x16x32_bf16 v[114:117], v[180:183], v[188:191], v[114:117]
	v_mfma_f32_16x16x32_bf16 v[102:105], v[168:171], v[192:195], v[102:105]
	v_mfma_f32_16x16x32_bf16 v[102:105], v[172:175], v[196:199], v[102:105]
	v_mfma_f32_16x16x32_bf16 v[98:101], v[176:179], v[192:195], v[98:101]
	v_mfma_f32_16x16x32_bf16 v[98:101], v[180:183], v[196:199], v[98:101]
	v_mfma_f32_16x16x32_bf16 v[86:89], v[168:171], v[200:203], v[86:89]
	v_mfma_f32_16x16x32_bf16 v[86:89], v[172:175], v[204:207], v[86:89]
	v_mfma_f32_16x16x32_bf16 v[82:85], v[176:179], v[200:203], v[82:85]
	v_mfma_f32_16x16x32_bf16 v[82:85], v[180:183], v[204:207], v[82:85]
	v_mfma_f32_16x16x32_bf16 v[70:73], v[168:171], v[208:211], v[70:73]
	v_mfma_f32_16x16x32_bf16 v[70:73], v[172:175], v[232:235], v[70:73]
	v_mfma_f32_16x16x32_bf16 v[66:69], v[176:179], v[208:211], v[66:69]
	v_mfma_f32_16x16x32_bf16 v[66:69], v[180:183], v[232:235], v[66:69]
	s_setprio 0
	s_barrier
	s_add_i32 s22, s24, s16
	v_lshl_add_u64 v[148:149], s[48:49], 0, v[134:135]
	s_mov_b32 m0, s22
	ds_read_b128 v[184:187], v154 offset:16384
	ds_read_b128 v[188:191], v154 offset:17408
	ds_read_b128 v[192:195], v154 offset:18432
	ds_read_b128 v[196:199], v154 offset:19456
	ds_read_b128 v[200:203], v154 offset:20480
	ds_read_b128 v[204:207], v154 offset:21504
	ds_read_b128 v[208:211], v154 offset:22528
	ds_read_b128 v[232:235], v154 offset:23552
	global_load_lds_dwordx4 v[148:149], off
	s_add_i32 m0, s22, 0x2000
	s_add_u32 s22, s48, 0x80000
	v_lshl_add_u64 v[212:213], s[48:49], 0, v[130:131]
	s_addc_u32 s23, s49, 0
	s_add_i32 s24, s25, s16
	global_load_lds_dwordx4 v[212:213], off
	v_lshl_add_u64 v[236:237], s[22:23], 0, v[134:135]
	s_mov_b32 m0, s24
	v_lshl_add_u64 v[238:239], s[50:51], 0, v[132:133]
	global_load_lds_dwordx4 v[236:237], off
	v_lshl_add_u64 v[236:237], s[22:23], 0, v[130:131]
	s_add_i32 m0, s24, 0x2000
	s_nop 0
	global_load_lds_dwordx4 v[236:237], off
	v_lshl_add_u64 v[236:237], s[50:51], 0, v[136:137]
	s_mov_b32 m0, s3
	s_nop 0
	global_load_lds_dwordx4 v[236:237], off
	s_mov_b32 m0, s55
	s_nop 0
	global_load_lds_dwordx4 v[238:239], off
	s_waitcnt vmcnt(8)
	s_waitcnt lgkmcnt(0)
	s_barrier
	s_setprio 1
	s_waitcnt lgkmcnt(0)
	v_mfma_f32_16x16x32_bf16 v[62:65], v[144:147], v[184:187], v[62:65]
	v_mfma_f32_16x16x32_bf16 v[62:65], v[156:159], v[188:191], v[62:65]
	v_mfma_f32_16x16x32_bf16 v[58:61], v[160:163], v[184:187], v[58:61]
	v_mfma_f32_16x16x32_bf16 v[58:61], v[164:167], v[188:191], v[58:61]
	v_mfma_f32_16x16x32_bf16 v[46:49], v[144:147], v[192:195], v[46:49]
	v_mfma_f32_16x16x32_bf16 v[46:49], v[156:159], v[196:199], v[46:49]
	v_mfma_f32_16x16x32_bf16 v[42:45], v[160:163], v[192:195], v[42:45]
	v_mfma_f32_16x16x32_bf16 v[42:45], v[164:167], v[196:199], v[42:45]
	v_mfma_f32_16x16x32_bf16 v[30:33], v[144:147], v[200:203], v[30:33]
	v_mfma_f32_16x16x32_bf16 v[30:33], v[156:159], v[204:207], v[30:33]
	v_mfma_f32_16x16x32_bf16 v[26:29], v[160:163], v[200:203], v[26:29]
	v_mfma_f32_16x16x32_bf16 v[26:29], v[164:167], v[204:207], v[26:29]
	v_mfma_f32_16x16x32_bf16 v[14:17], v[144:147], v[208:211], v[14:17]
	v_mfma_f32_16x16x32_bf16 v[14:17], v[156:159], v[232:235], v[14:17]
	v_mfma_f32_16x16x32_bf16 v[10:13], v[160:163], v[208:211], v[10:13]
	v_mfma_f32_16x16x32_bf16 v[10:13], v[164:167], v[232:235], v[10:13]
	s_setprio 0
	s_setprio 1
	v_mfma_f32_16x16x32_bf16 v[54:57], v[168:171], v[184:187], v[54:57]
	v_mfma_f32_16x16x32_bf16 v[54:57], v[172:175], v[188:191], v[54:57]
	v_mfma_f32_16x16x32_bf16 v[50:53], v[176:179], v[184:187], v[50:53]
	v_mfma_f32_16x16x32_bf16 v[50:53], v[180:183], v[188:191], v[50:53]
	v_mfma_f32_16x16x32_bf16 v[38:41], v[168:171], v[192:195], v[38:41]
	v_mfma_f32_16x16x32_bf16 v[38:41], v[172:175], v[196:199], v[38:41]
	v_mfma_f32_16x16x32_bf16 v[34:37], v[176:179], v[192:195], v[34:37]
	v_mfma_f32_16x16x32_bf16 v[34:37], v[180:183], v[196:199], v[34:37]
	v_mfma_f32_16x16x32_bf16 v[22:25], v[168:171], v[200:203], v[22:25]
	v_mfma_f32_16x16x32_bf16 v[22:25], v[172:175], v[204:207], v[22:25]
	v_mfma_f32_16x16x32_bf16 v[18:21], v[176:179], v[200:203], v[18:21]
	v_mfma_f32_16x16x32_bf16 v[18:21], v[180:183], v[204:207], v[18:21]
	v_mfma_f32_16x16x32_bf16 v[6:9], v[168:171], v[208:211], v[6:9]
	v_mfma_f32_16x16x32_bf16 v[6:9], v[172:175], v[232:235], v[6:9]
	v_mfma_f32_16x16x32_bf16 v[2:5], v[176:179], v[208:211], v[2:5]
	v_mfma_f32_16x16x32_bf16 v[2:5], v[180:183], v[232:235], v[2:5]
	s_setprio 0
	s_barrier
	s_add_i32 s24, 0, 0x18000
	v_add_u32_e32 v155, s24, v152
	s_add_i32 s25, 0, 0x1c000
	ds_read_b128 v[144:147], v155
	ds_read_b128 v[156:159], v155 offset:1024
	ds_read_b128 v[160:163], v155 offset:2048
	ds_read_b128 v[164:167], v155 offset:3072
	v_add_u32_e32 v155, s25, v152
	ds_read_b128 v[168:171], v155
	ds_read_b128 v[172:175], v155 offset:1024
	ds_read_b128 v[176:179], v155 offset:2048
	ds_read_b128 v[180:183], v155 offset:3072
	s_add_u32 s22, s50, 0x80000
	s_addc_u32 s23, s51, 0
	s_mov_b32 m0, s57
	v_lshl_add_u64 v[240:241], s[22:23], 0, v[136:137]
	ds_read_b128 v[184:187], v154 offset:32768
	ds_read_b128 v[188:191], v154 offset:33792
	ds_read_b128 v[192:195], v154 offset:34816
	ds_read_b128 v[196:199], v154 offset:35840
	ds_read_b128 v[200:203], v154 offset:36864
	ds_read_b128 v[204:207], v154 offset:37888
	ds_read_b128 v[208:211], v154 offset:38912
	ds_read_b128 v[232:235], v154 offset:39936
	global_load_lds_dwordx4 v[240:241], off
	v_lshl_add_u64 v[240:241], s[22:23], 0, v[132:133]
	s_mov_b32 m0, s68
	s_nop 0
	global_load_lds_dwordx4 v[240:241], off
	s_waitcnt vmcnt(8)
	s_waitcnt lgkmcnt(0)
	s_barrier
	s_setprio 1
	s_waitcnt lgkmcnt(0)
	v_mfma_f32_16x16x32_bf16 v[126:129], v[144:147], v[184:187], v[126:129]
	v_mfma_f32_16x16x32_bf16 v[126:129], v[156:159], v[188:191], v[126:129]
	v_mfma_f32_16x16x32_bf16 v[122:125], v[160:163], v[184:187], v[122:125]
	v_mfma_f32_16x16x32_bf16 v[122:125], v[164:167], v[188:191], v[122:125]
	v_mfma_f32_16x16x32_bf16 v[110:113], v[144:147], v[192:195], v[110:113]
	v_mfma_f32_16x16x32_bf16 v[110:113], v[156:159], v[196:199], v[110:113]
	v_mfma_f32_16x16x32_bf16 v[106:109], v[160:163], v[192:195], v[106:109]
	v_mfma_f32_16x16x32_bf16 v[106:109], v[164:167], v[196:199], v[106:109]
	v_mfma_f32_16x16x32_bf16 v[94:97], v[144:147], v[200:203], v[94:97]
	v_mfma_f32_16x16x32_bf16 v[94:97], v[156:159], v[204:207], v[94:97]
	v_mfma_f32_16x16x32_bf16 v[90:93], v[160:163], v[200:203], v[90:93]
	v_mfma_f32_16x16x32_bf16 v[90:93], v[164:167], v[204:207], v[90:93]
	v_mfma_f32_16x16x32_bf16 v[78:81], v[144:147], v[208:211], v[78:81]
	v_mfma_f32_16x16x32_bf16 v[78:81], v[156:159], v[232:235], v[78:81]
	v_mfma_f32_16x16x32_bf16 v[74:77], v[160:163], v[208:211], v[74:77]
	v_mfma_f32_16x16x32_bf16 v[74:77], v[164:167], v[232:235], v[74:77]
	s_setprio 0
	s_setprio 1
	v_mfma_f32_16x16x32_bf16 v[118:121], v[168:171], v[184:187], v[118:121]
	v_mfma_f32_16x16x32_bf16 v[118:121], v[172:175], v[188:191], v[118:121]
	v_mfma_f32_16x16x32_bf16 v[114:117], v[176:179], v[184:187], v[114:117]
	v_mfma_f32_16x16x32_bf16 v[114:117], v[180:183], v[188:191], v[114:117]
	v_mfma_f32_16x16x32_bf16 v[102:105], v[168:171], v[192:195], v[102:105]
	v_mfma_f32_16x16x32_bf16 v[102:105], v[172:175], v[196:199], v[102:105]
	v_mfma_f32_16x16x32_bf16 v[98:101], v[176:179], v[192:195], v[98:101]
	v_mfma_f32_16x16x32_bf16 v[98:101], v[180:183], v[196:199], v[98:101]
	v_mfma_f32_16x16x32_bf16 v[86:89], v[168:171], v[200:203], v[86:89]
	v_mfma_f32_16x16x32_bf16 v[86:89], v[172:175], v[204:207], v[86:89]
	v_mfma_f32_16x16x32_bf16 v[82:85], v[176:179], v[200:203], v[82:85]
	v_mfma_f32_16x16x32_bf16 v[82:85], v[180:183], v[204:207], v[82:85]
	v_mfma_f32_16x16x32_bf16 v[70:73], v[168:171], v[208:211], v[70:73]
	v_mfma_f32_16x16x32_bf16 v[70:73], v[172:175], v[232:235], v[70:73]
	v_mfma_f32_16x16x32_bf16 v[66:69], v[176:179], v[208:211], v[66:69]
	v_mfma_f32_16x16x32_bf16 v[66:69], v[180:183], v[232:235], v[66:69]
	s_setprio 0
	s_barrier
	s_add_i32 s22, s24, s16
	v_lshl_add_u64 v[148:149], v[148:149], 0, s[62:63]
	s_mov_b32 m0, s22
	ds_read_b128 v[184:187], v154 offset:49152
	ds_read_b128 v[188:191], v154 offset:50176
	ds_read_b128 v[192:195], v154 offset:51200
	ds_read_b128 v[196:199], v154 offset:52224
	ds_read_b128 v[200:203], v154 offset:53248
	ds_read_b128 v[204:207], v154 offset:54272
	ds_read_b128 v[208:211], v154 offset:55296
	ds_read_b128 v[232:235], v154 offset:56320
	global_load_lds_dwordx4 v[148:149], off
	s_add_i32 m0, s22, 0x2000
	s_add_u32 s22, s48, 0x80080
	v_lshl_add_u64 v[148:149], v[212:213], 0, s[62:63]
	s_addc_u32 s23, s49, 0
	s_add_i32 s24, s25, s16
	global_load_lds_dwordx4 v[148:149], off
	v_lshl_add_u64 v[148:149], s[22:23], 0, v[134:135]
	s_mov_b32 m0, s24
	s_nop 0
	global_load_lds_dwordx4 v[148:149], off
	v_lshl_add_u64 v[148:149], s[22:23], 0, v[130:131]
	s_add_i32 m0, s24, 0x2000
	s_nop 0
	global_load_lds_dwordx4 v[148:149], off
	v_lshl_add_u64 v[148:149], v[236:237], 0, s[62:63]
	s_mov_b32 m0, s69
	s_nop 0
	global_load_lds_dwordx4 v[148:149], off
	v_lshl_add_u64 v[148:149], v[238:239], 0, s[62:63]
	s_mov_b32 m0, s70
	s_nop 0
	global_load_lds_dwordx4 v[148:149], off
	s_waitcnt vmcnt(8)
	s_waitcnt lgkmcnt(0)
	s_barrier
	s_setprio 1
	s_waitcnt lgkmcnt(0)
	v_mfma_f32_16x16x32_bf16 v[62:65], v[144:147], v[184:187], v[62:65]
	v_mfma_f32_16x16x32_bf16 v[62:65], v[156:159], v[188:191], v[62:65]
	v_mfma_f32_16x16x32_bf16 v[58:61], v[160:163], v[184:187], v[58:61]
	v_mfma_f32_16x16x32_bf16 v[58:61], v[164:167], v[188:191], v[58:61]
	v_mfma_f32_16x16x32_bf16 v[46:49], v[144:147], v[192:195], v[46:49]
	v_mfma_f32_16x16x32_bf16 v[46:49], v[156:159], v[196:199], v[46:49]
	v_mfma_f32_16x16x32_bf16 v[42:45], v[160:163], v[192:195], v[42:45]
	v_mfma_f32_16x16x32_bf16 v[42:45], v[164:167], v[196:199], v[42:45]
	v_mfma_f32_16x16x32_bf16 v[30:33], v[144:147], v[200:203], v[30:33]
	v_mfma_f32_16x16x32_bf16 v[30:33], v[156:159], v[204:207], v[30:33]
	v_mfma_f32_16x16x32_bf16 v[26:29], v[160:163], v[200:203], v[26:29]
	v_mfma_f32_16x16x32_bf16 v[26:29], v[164:167], v[204:207], v[26:29]
	v_mfma_f32_16x16x32_bf16 v[14:17], v[144:147], v[208:211], v[14:17]
	v_mfma_f32_16x16x32_bf16 v[14:17], v[156:159], v[232:235], v[14:17]
	v_mfma_f32_16x16x32_bf16 v[10:13], v[160:163], v[208:211], v[10:13]
	v_mfma_f32_16x16x32_bf16 v[10:13], v[164:167], v[232:235], v[10:13]
	s_setprio 0
	s_setprio 1
	v_mfma_f32_16x16x32_bf16 v[54:57], v[168:171], v[184:187], v[54:57]
	v_mfma_f32_16x16x32_bf16 v[54:57], v[172:175], v[188:191], v[54:57]
	v_mfma_f32_16x16x32_bf16 v[50:53], v[176:179], v[184:187], v[50:53]
	v_mfma_f32_16x16x32_bf16 v[50:53], v[180:183], v[188:191], v[50:53]
	v_mfma_f32_16x16x32_bf16 v[38:41], v[168:171], v[192:195], v[38:41]
	v_mfma_f32_16x16x32_bf16 v[38:41], v[172:175], v[196:199], v[38:41]
	v_mfma_f32_16x16x32_bf16 v[34:37], v[176:179], v[192:195], v[34:37]
	v_mfma_f32_16x16x32_bf16 v[34:37], v[180:183], v[196:199], v[34:37]
	v_mfma_f32_16x16x32_bf16 v[22:25], v[168:171], v[200:203], v[22:25]
	v_mfma_f32_16x16x32_bf16 v[22:25], v[172:175], v[204:207], v[22:25]
	v_mfma_f32_16x16x32_bf16 v[18:21], v[176:179], v[200:203], v[18:21]
	v_mfma_f32_16x16x32_bf16 v[18:21], v[180:183], v[204:207], v[18:21]
	v_mfma_f32_16x16x32_bf16 v[6:9], v[168:171], v[208:211], v[6:9]
	v_mfma_f32_16x16x32_bf16 v[6:9], v[172:175], v[232:235], v[6:9]
	v_mfma_f32_16x16x32_bf16 v[2:5], v[176:179], v[208:211], v[2:5]
	v_mfma_f32_16x16x32_bf16 v[2:5], v[180:183], v[232:235], v[2:5]
	s_setprio 0
	s_barrier
	s_add_i32 s21, s21, 2
	s_add_u32 s46, s46, 0x100
	s_addc_u32 s47, s47, 0
	s_add_u32 s19, s19, 0x100
	s_addc_u32 s20, s20, 0
	s_cmp_gt_u32 s21, 29
	s_cbranch_scc0 .LBB0_340
	s_and_b64 vcc, exec, s[8:9]
	s_cbranch_vccz .LBB0_343
	s_barrier
